# v90: v88 + next-unit queue ticket requested at key-loop end + differential-head first-tile DMA issued before the query-fragment wait
# baseline (speedup 1.0000x reference)
; #define LAS __attribute__((address_space(3)))
; #define ATT_WAITV(n) asm volatile("s_waitcnt vmcnt(" #n ")" ::: "memory")
; template <int MODE>
; __device__ __forceinline__ void attn_unit(const Params& P, LAS unsigned char* lds, const int b, const int h, const int qb) {
;     ...
;     { const bf16_t* qp = Qb + (size_t)q * RS + (FOX ? 0 : 64 * mp) + 8 * hh;
; #pragma unroll
;       for (int ks = 0; ks < NQ; ++ks) Qf[ks] = *(const bf16x8*)(qp + 16 * ks); }
;     const int nt = (q0 + ROWS) / 64;
;     int kt0 = 0;
;     const float* Cl = (const float*)(P.ws + WS_C) + (size_t)(b * 8 + h) * S_;
;     if (FOX) {
;         const int kd = q0 / 64; int pred = 0;
;         if (tid < kd) pred = (tab[TAB_AQ2] + Cl[q0] - Cl[tid * 64 + 63] >= -150.0f) ? 1 : 0;
;         kt0 = kd - __syncthreads_count(pred);
;     } else {
;         if (tid < 129) ((LAS float*)(lds + AL_BIAS))[tid] = tab[h * 132 + tid] - tab[h * 132 + 128];
;     }
;     const int krow = 4 * w + (lane >> 4), kchunk = (lane & 15) ^ (krow & 15);
;     const bf16_t* kg = Kb_ + (size_t)krow * RS + kchunk * 8;
;     const int vst = 2 * w + (lane >> 5), vkey = (vst >> 2) * 8 + ((lane >> 2) & 7);
;     const bf16_t* vg = Vb_ + (size_t)vkey * RS + (vst & 3) * 32 + (lane & 3) * 8;
;     const float* cg_ = Cl + lane;
;     ...
;     const int pr = (r & 19) | ((r & 4) << 1) | ((r & 8) >> 1);
;     const unsigned kra = pr * 256, kswz = pr & 15;
;     const unsigned vra = 16384 + hh * 2048 + ((lane & 15) >> 2) * 64 + ((lane >> 4) & 1) * 32 + (lane & 3) * 8;
;     f32x16 O[4];
; #pragma unroll
;     for (int d = 0; d < 4; ++d)
; #pragma unroll
;         for (int i = 0; i < 16; ++i) O[d][i] = 0.f;
;     float m1 = ONLINE ? -INFINITY : 0.f, l1 = 0.f;
;     const int ktw_last = (q0w + 31) / 64;
;     ATT_WAITV(0); __builtin_amdgcn_s_barrier(); asm volatile("" ::: "memory");
; #pragma unroll
;     for (int i = 0; i < AL_PD; ++i) if (kt0 + i < nt) ATT_DMA(kt0 + i, i);
.LBB0_466:
	s_and_b64 vcc, exec, s[8:9]
	s_cbranch_vccz .LBB0_420
	s_lshl_b32 s0, s11, 2
	s_lshr_b32 s97, s10, 6
	s_and_b32 s10, s10, 63
	s_lshr_b32 s12, s11, 1
	s_and_b32 s98, s0, 4
	s_or_b32 s96, s98, s97
	s_lshl_b32 s0, s10, 7
	s_lshl_b32 s33, s12, 3
	s_xor_b32 s99, s0, 0x1f80
	s_or_b32 s0, s96, s33
	s_mov_b32 s1, s13
	s_lshl_b64 s[8:9], s[0:1], 20
	s_lshl_b64 s[0:1], s[0:1], 21
	s_add_u32 s64, s86, s0
	s_addc_u32 s65, s87, s1
	s_andn2_b64 vcc, exec, s[6:7]
	s_mov_b64 s[66:67], -1
	s_cbranch_vccnz .LBB0_497
	v_mov_b32_e32 v6, v178
	v_mov_b32_e32 v151, v1
	v_readfirstlane_b32 s58, v6
	s_ashr_i32 s11, s58, 6
	s_and_b32 s0, s11, 3
	s_lshl_b32 s38, s0, 5
	v_and_b32_e32 v8, 31, v6
	s_or_b32 s59, s38, s99
	s_ashr_i32 s1, s58, 8
	v_or_b32_e32 v162, s59, v8
	v_lshlrev_b32_e32 v0, 8, v162
	s_lshl_b32 s22, s1, 6
	v_bfe_u32 v7, v6, 5, 1
	v_lshl_add_u64 v[2:3], s[64:65], 0, v[0:1]
	s_ashr_i32 s23, s22, 31
	v_lshl_add_u64 v[2:3], s[22:23], 1, v[2:3]
	v_lshlrev_b32_e32 v150, 4, v7
	v_lshl_add_u64 v[2:3], v[2:3], 0, v[150:151]
	global_load_dwordx4 v[112:115], v[2:3], off
	global_load_dwordx4 v[116:119], v[2:3], off offset:32
	global_load_dwordx4 v[120:123], v[2:3], off offset:64
	global_load_dwordx4 v[124:127], v[2:3], off offset:96
	s_lshl_b64 s[66:67], s[8:9], 1
	s_add_u32 s40, s88, s66
	s_addc_u32 s41, s89, s67
	v_and_b32_e32 v151, 63, v6
	s_add_u32 s68, s90, s66
	s_addc_u32 s69, s91, s67
	s_lshl_b32 s39, s11, 2
	v_lshrrev_b32_e32 v10, 4, v151
	v_or_b32_e32 v2, s39, v10
	s_ashr_i32 s22, s58, 4
	v_lshrrev_b32_e32 v0, 2, v6
	v_bitop3_b32 v9, s39, v6, v10 bitop3:0x36
	v_ashrrev_i32_e32 v3, 31, v2
	s_lshl_b32 s23, s11, 1
	v_bfi_b32 v4, -8, s22, v0
	v_lshlrev_b32_e32 v0, 3, v6
	v_lshlrev_b64 v[2:3], 8, v[2:3]
	v_ashrrev_i32_e32 v5, 31, v4
	v_and_or_b32 v11, s23, 2, v7
	v_and_b32_e32 v156, 24, v0
	v_lshlrev_b32_e32 v0, 4, v9
	s_lshl_b32 s23, s11, 10
	v_lshlrev_b64 v[12:13], 8, v[4:5]
	v_lshl_add_u64 v[2:3], s[40:41], 0, v[2:3]
	v_and_b32_e32 v0, 0xf0, v0
	s_add_i32 s77, s23, 0x100
	v_lshl_add_u64 v[4:5], v[2:3], 0, v[0:1]
	v_lshl_add_u64 v[2:3], s[68:69], 0, v[12:13]
	v_lshlrev_b32_e32 v0, 6, v11
	s_mov_b32 m0, s77
	v_lshl_add_u64 v[2:3], v[2:3], 0, v[0:1]
	v_lshlrev_b32_e32 v0, 1, v156
	global_load_lds_dwordx4 v[4:5], off
	v_lshl_add_u64 v[12:13], v[4:5], 0, s[28:29]
	s_add_i32 m0, s77, 0x2000
	v_lshl_add_u64 v[2:3], v[2:3], 0, v[0:1]
	global_load_lds_dwordx4 v[12:13], off
	s_add_i32 m0, s77, 0x4000
	v_lshl_add_u64 v[12:13], v[2:3], 0, s[28:29]
	global_load_lds_dwordx4 v[2:3], off
	s_add_i32 m0, s77, 0x6000
	s_nop 0
	global_load_lds_dwordx4 v[12:13], off
	s_add_i32 m0, s77, 0x8000
	v_lshl_add_u64 v[12:13], v[4:5], 0, s[30:31]
	global_load_lds_dwordx4 v[12:13], off
	v_lshl_add_u64 v[12:13], v[4:5], 0, s[36:37]
	s_add_i32 m0, s77, 0xa000
	s_nop 0
	global_load_lds_dwordx4 v[12:13], off
	v_lshl_add_u64 v[12:13], v[2:3], 0, s[30:31]
	s_add_i32 m0, s77, 0xc000
	s_nop 0
	global_load_lds_dwordx4 v[12:13], off
	v_lshl_add_u64 v[12:13], v[2:3], 0, s[36:37]
	s_add_i32 m0, s77, 0xe000
	s_cmp_eq_u32 s10, 63
	global_load_lds_dwordx4 v[12:13], off
	s_cbranch_scc1 .LBB0_472
	s_mov_b64 s[40:41], 0x8000
	s_add_i32 m0, s77, 0x10000
	v_lshl_add_u64 v[12:13], v[4:5], 0, s[40:41]
	s_mov_b64 s[68:69], 0xa000
	global_load_lds_dwordx4 v[12:13], off
	v_lshl_add_u64 v[4:5], v[4:5], 0, s[68:69]
	s_add_i32 m0, s77, 0x12000
	s_nop 0
	global_load_lds_dwordx4 v[4:5], off
	v_lshl_add_u64 v[4:5], v[2:3], 0, s[40:41]
	s_add_i32 m0, s77, 0x14000
	v_lshl_add_u64 v[2:3], v[2:3], 0, s[68:69]
	global_load_lds_dwordx4 v[4:5], off
	s_add_i32 m0, s77, 0x16000
	s_nop 0
	global_load_lds_dwordx4 v[2:3], off
; #define LAS __attribute__((address_space(3)))
; #define ATT_WAITV(n) asm volatile("s_waitcnt vmcnt(" #n ")" ::: "memory")
; template <int MODE>
; __device__ __forceinline__ void attn_unit(const Params& P, LAS unsigned char* lds, const int b, const int h, const int qb) {
;     ...
;         if (tid < 129) ((LAS float*)(lds + AL_BIAS))[tid] = tab[h * 132 + tid] - tab[h * 132 + 128];
;     }
;     const int krow = 4 * w + (lane >> 4), kchunk = (lane & 15) ^ (krow & 15);
;     const bf16_t* kg = Kb_ + (size_t)krow * RS + kchunk * 8;
;     const int vst = 2 * w + (lane >> 5), vkey = (vst >> 2) * 8 + ((lane >> 2) & 7);
;     const bf16_t* vg = Vb_ + (size_t)vkey * RS + (vst & 3) * 32 + (lane & 3) * 8;
;     const float* cg_ = Cl + lane;
;     ...
;     const int pr = (r & 19) | ((r & 4) << 1) | ((r & 8) >> 1);
;     const unsigned kra = pr * 256, kswz = pr & 15;
;     const unsigned vra = 16384 + hh * 2048 + ((lane & 15) >> 2) * 64 + ((lane >> 4) & 1) * 32 + (lane & 3) * 8;
;     f32x16 O[4];
; #pragma unroll
;     for (int d = 0; d < 4; ++d)
; #pragma unroll
;         for (int i = 0; i < 16; ++i) O[d][i] = 0.f;
;     float m1 = ONLINE ? -INFINITY : 0.f, l1 = 0.f;
;     const int ktw_last = (q0w + 31) / 64;
;     ATT_WAITV(0); __builtin_amdgcn_s_barrier(); asm volatile("" ::: "memory");
; #pragma unroll
;     for (int i = 0; i < AL_PD; ++i) if (kt0 + i < nt) ATT_DMA(kt0 + i, i);
.LBB0_472:
	v_cmp_gt_i32_e32 vcc, s75, v6
	s_and_saveexec_b64 s[40:41], vcc
	s_cbranch_execz .Lm1_bias_done
	s_mul_i32 s70, s96, 0x84
	v_add_u32_e32 v2, s70, v6
	s_mov_b32 s71, s13
	v_ashrrev_i32_e32 v3, 31, v2
	s_lshl_b64 s[70:71], s[70:71], 2
	v_lshl_add_u64 v[2:3], v[2:3], 2, s[56:57]
	s_add_u32 s70, s56, s70
	s_addc_u32 s71, s57, s71
	global_load_dword v0, v[2:3], off
	s_nop 0
	global_load_dword v2, v1, s[70:71] offset:512
	v_lshl_add_u32 v3, v6, 2, v232
	s_waitcnt vmcnt(0)
	v_sub_f32_e32 v0, v0, v2
	v_add_u32_e32 v2, 0x22100, v3
	ds_write_b32 v2, v0
.Lm1_bias_done:
	s_or_b64 exec, exec, s[40:41]
	s_waitcnt vmcnt(0)
	s_barrier
	v_and_b32_e32 v2, 19, v6
	v_lshlrev_b32_e32 v3, 1, v6
	v_and_or_b32 v2, v3, 8, v2
	v_lshrrev_b32_e32 v3, 1, v6
	v_and_b32_e32 v3, 4, v3
	v_or_b32_e32 v4, v2, v3
	v_bitop3_b32 v2, v2, 15, v3 bitop3:0xc8
	v_lshlrev_b32_e32 v3, 4, v6
	v_and_b32_e32 v160, 0xc0, v3
	v_lshl_or_b32 v3, s1, 3, v7
	v_lshlrev_b32_e32 v159, 8, v4
	v_bitop3_b32 v4, v4, v3, 15 bitop3:0x6c
	v_lshlrev_b32_e32 v161, 4, v4
	v_bitop3_b32 v4, v3, v2, 2 bitop3:0x36
	v_lshlrev_b32_e32 v164, 4, v4
	v_bitop3_b32 v4, v3, v2, 4 bitop3:0x36
	v_bitop3_b32 v2, v3, v2, 6 bitop3:0x36
	s_add_i32 s38, s99, s38
	v_lshlrev_b32_e32 v148, 3, v7
	v_lshlrev_b32_e32 v166, 4, v2
	v_add_u32_e32 v2, s38, v8
	v_sub_u32_e32 v167, v2, v148
	v_add_u32_e32 v2, s39, v10
	v_ashrrev_i32_e32 v3, 31, v2
	v_lshlrev_b32_e32 v165, 4, v4
	v_lshlrev_b64 v[2:3], 8, v[2:3]
	v_and_b32_e32 v4, 15, v9
	s_and_b32 s70, s22, -8
	v_bfe_u32 v0, v6, 2, 3
	s_add_i32 s38, s97, s33
	v_lshl_or_b32 v2, v4, 4, v2
	s_add_i32 s40, s38, s98
	v_lshl_add_u64 v[152:153], s[52:53], 0, v[2:3]
	v_add_u32_e32 v2, s70, v0
	s_lshl_b32 s38, s58, 1
	v_ashrrev_i32_e32 v3, 31, v2
	v_and_b32_e32 v0, 3, v6
	s_and_b32 s38, s38, 0x80
	v_lshlrev_b64 v[2:3], 8, v[2:3]
	v_lshlrev_b32_e32 v0, 4, v0
	v_lshl_or_b32 v4, v7, 6, s38
	v_lshlrev_b32_e32 v5, 5, v10
	v_or3_b32 v2, v2, v0, v4
	v_mov_b32_e32 v14, v1
	v_mov_b32_e32 v15, v1
	v_lshlrev_b32_e32 v157, 11, v7
	v_and_b32_e32 v158, 32, v5
	s_add_i32 s22, s99, 0x80
	s_mov_b32 s41, s13
	v_lshl_add_u64 v[154:155], s[52:53], 0, v[2:3]
	v_mov_b32_e32 v0, v1
	v_mov_b32_e32 v2, v1
	v_mov_b32_e32 v3, v1
	v_mov_b32_e32 v4, v1
	v_mov_b32_e32 v5, v1
	v_mov_b32_e32 v6, v1
	v_mov_b32_e32 v7, v1
	v_mov_b32_e32 v8, v1
	v_mov_b32_e32 v9, v1
	v_mov_b32_e32 v10, v1
	v_mov_b32_e32 v11, v1
	v_mov_b32_e32 v12, v1
	v_mov_b32_e32 v13, v1
	v_mov_b64_e32 v[30:31], v[14:15]
	v_mov_b64_e32 v[46:47], v[14:15]
	v_mov_b64_e32 v[62:63], v[14:15]
	v_mov_b64_e32 v[78:79], v[14:15]
	v_lshlrev_b32_e32 v149, 7, v162
	s_lshr_b32 s22, s22, 6
	s_lshr_b32 s23, s59, 6
	s_add_i32 s75, s59, 0xffffff41
	s_lshl_b64 s[68:69], s[40:41], 21
	s_mov_b32 s38, 0
	v_mov_b32_e32 v163, 0
	s_mov_b32 s39, 63
	v_mov_b64_e32 v[28:29], v[12:13]
	v_mov_b64_e32 v[26:27], v[10:11]
	v_mov_b64_e32 v[24:25], v[8:9]
	v_mov_b64_e32 v[22:23], v[6:7]
	v_mov_b64_e32 v[20:21], v[4:5]
	v_mov_b64_e32 v[18:19], v[2:3]
	v_mov_b64_e32 v[16:17], v[0:1]
	v_mov_b64_e32 v[44:45], v[12:13]
	v_mov_b64_e32 v[42:43], v[10:11]
	v_mov_b64_e32 v[40:41], v[8:9]
	v_mov_b64_e32 v[38:39], v[6:7]
	v_mov_b64_e32 v[36:37], v[4:5]
	v_mov_b64_e32 v[34:35], v[2:3]
	v_mov_b64_e32 v[32:33], v[0:1]
	v_mov_b64_e32 v[60:61], v[12:13]
	v_mov_b64_e32 v[58:59], v[10:11]
	v_mov_b64_e32 v[56:57], v[8:9]
	v_mov_b64_e32 v[54:55], v[6:7]
	v_mov_b64_e32 v[52:53], v[4:5]
	v_mov_b64_e32 v[50:51], v[2:3]
	v_mov_b64_e32 v[48:49], v[0:1]
	v_mov_b64_e32 v[76:77], v[12:13]
	v_mov_b64_e32 v[74:75], v[10:11]
	v_mov_b64_e32 v[72:73], v[8:9]
	v_mov_b64_e32 v[70:71], v[6:7]
	v_mov_b64_e32 v[68:69], v[4:5]
	v_mov_b64_e32 v[66:67], v[2:3]
	v_mov_b64_e32 v[64:65], v[0:1]
	s_mov_b32 s40, 0
	s_waitcnt vmcnt(0)
	s_branch .LBB0_475

; template <bool ONLINE, int NO>
; __device__ __forceinline__ void softmax_tile(f32x16 (&s)[2], float& m, float& l, f32x16 (&O)[NO], u32x4 (&pk)[4]) {
;     ...
;     float ps = 0.f;
; #pragma unroll
;     for (int blk = 0; blk < 2; ++blk)
; #pragma unroll
;         for (int i = 0; i < 16; ++i) { const float p = __builtin_amdgcn_exp2f(ONLINE ? (s[blk][i] - mn) : s[blk][i]); ps += p; s[blk][i] = p; }
;     l += ps;
; #pragma unroll
;     for (int blk = 0; blk < 2; ++blk)
; #pragma unroll
;         for (int sh = 0; sh < 2; ++sh) { u32x4 pw;
;             pw.x = cvt_pk_bf16(s[blk][8 * sh], s[blk][8 * sh + 1]); pw.y = cvt_pk_bf16(s[blk][8 * sh + 2], s[blk][8 * sh + 3]);
;             pw.z = cvt_pk_bf16(s[blk][8 * sh + 4], s[blk][8 * sh + 5]); pw.w = cvt_pk_bf16(s[blk][8 * sh + 6], s[blk][8 * sh + 7]); pk[2 * blk + sh] = pw; }
.LBB0_483:
	s_barrier
	s_cmpk_lt_u32 s58, 0x100
	s_cbranch_scc1 .LBB0_485
	s_cmp_eq_u32 s40, 0
	s_cbranch_scc1 .LmB_bar2
	s_add_i32 s41, s39, 0xffffff81
	s_cmp_le_i32 s41, s75
	s_cbranch_scc0 .LmB_bar2
	s_waitcnt lgkmcnt(8)
	v_mfma_f32_32x32x16_bf16 v[64:79], v[168:171], v[100:103], v[64:79]
	ds_read_b64_tr_b16 v[144:145], v0 offset:0x3000
	ds_read_b64_tr_b16 v[146:147], v0 offset:0x3100
	ds_read_b64_tr_b16 v[140:141], v0 offset:0x3200
	ds_read_b64_tr_b16 v[142:143], v0 offset:0x3300
	ds_read_b64_tr_b16 v[136:137], v0 offset:0x3400
	ds_read_b64_tr_b16 v[138:139], v0 offset:0x3500
	ds_read_b64_tr_b16 v[132:133], v0 offset:0x3600
	ds_read_b64_tr_b16 v[134:135], v0 offset:0x3700
	v_mfma_f32_32x32x16_bf16 v[48:63], v[10:13], v[100:103], v[48:63]
	v_exp_f32_e32 v104, v80
	v_exp_f32_e32 v105, v81
	v_exp_f32_e32 v106, v82
	v_mfma_f32_32x32x16_bf16 v[32:47], v[180:183], v[100:103], v[32:47]
	v_exp_f32_e32 v107, v83
	v_exp_f32_e32 v108, v84
	v_exp_f32_e32 v109, v85
	v_mfma_f32_32x32x16_bf16 v[16:31], v[2:5], v[100:103], v[16:31]
	v_exp_f32_e32 v110, v86
	v_exp_f32_e32 v111, v87
	v_cvt_pk_bf16_f32 v80, v104, v105
	v_cvt_pk_bf16_f32 v81, v106, v107
	v_cvt_pk_bf16_f32 v82, v108, v109
	v_add_f32_e32 v14, v242, v14
	v_cvt_pk_bf16_f32 v83, v110, v111
	v_add_f32_e32 v14, v243, v14
	s_waitcnt lgkmcnt(8)
	v_mfma_f32_32x32x16_bf16 v[64:79], v[6:9], v[80:83], v[64:79]
	v_exp_f32_e32 v2, v88
	v_exp_f32_e32 v3, v89
	v_exp_f32_e32 v4, v90
	v_mfma_f32_32x32x16_bf16 v[48:63], v[128:131], v[80:83], v[48:63]
	v_exp_f32_e32 v5, v91
	v_exp_f32_e32 v10, v92
	v_exp_f32_e32 v11, v93
	v_mfma_f32_32x32x16_bf16 v[32:47], v[172:175], v[80:83], v[32:47]
	v_exp_f32_e32 v12, v94
	v_exp_f32_e32 v13, v95
	v_add_f32_e32 v14, v244, v14
	v_add_f32_e32 v14, v245, v14
	v_mfma_f32_32x32x16_bf16 v[16:31], v[184:187], v[80:83], v[16:31]
	v_cvt_pk_bf16_f32 v84, v2, v3
	v_cvt_pk_bf16_f32 v85, v4, v5
	v_cvt_pk_bf16_f32 v86, v10, v11
	v_add_f32_e32 v14, v246, v14
	v_cvt_pk_bf16_f32 v87, v12, v13
	v_add_f32_e32 v14, v247, v14
	v_add_f32_e32 v14, v248, v14
	s_waitcnt lgkmcnt(0)
	v_add_f32_e32 v14, v249, v14
	v_add_f32_e32 v14, v250, v14
	v_add_f32_e32 v14, v251, v14
	v_add_f32_e32 v14, v252, v14
	v_add_f32_e32 v14, v236, v14
	v_mfma_f32_32x32x16_bf16 v[64:79], v[144:147], v[84:87], v[64:79]
	v_add_f32_e32 v14, v104, v14
	v_add_f32_e32 v14, v105, v14
	v_add_f32_e32 v14, v106, v14
	v_add_f32_e32 v14, v107, v14
	v_add_f32_e32 v14, v108, v14
	v_add_f32_e32 v14, v109, v14
	v_mfma_f32_32x32x16_bf16 v[48:63], v[140:143], v[84:87], v[48:63]
	v_add_f32_e32 v14, v110, v14
	v_add_f32_e32 v14, v111, v14
	v_add_f32_e32 v14, v2, v14
	v_add_f32_e32 v14, v3, v14
	v_add_f32_e32 v14, v4, v14
	v_add_f32_e32 v14, v5, v14
	v_mfma_f32_32x32x16_bf16 v[32:47], v[136:139], v[84:87], v[32:47]
	v_add_f32_e32 v14, v10, v14
	v_add_f32_e32 v14, v11, v14
	v_add_f32_e32 v14, v12, v14
	v_add_f32_e32 v14, v13, v14
	v_add_f32_e32 v163, v163, v14
	v_mfma_f32_32x32x16_bf16 v[16:31], v[132:135], v[84:87], v[16:31]


; template <int MODE>
; __device__ __forceinline__ void attn_unit(const Params& P, LAS unsigned char* lds, const int b, const int h, const int qb) {
;     ...
;             if constexpr (MODE == 1) {
;                 bf16x8 kf[8];
;                 const unsigned kb_ = (unsigned)(uintptr_t)Kb + kra, c0 = mp * 8 + hh;
;                 k_issue4(kf, kb_ + (((c0) ^ kswz) << 4), kb_ + (((c0 + 2) ^ kswz) << 4), kb_ + (((c0 + 4) ^ kswz) << 4), kb_ + (((c0 + 6) ^ kswz) << 4));
;                 v_issue<0>(va, vaddr);
;                 k_wait<8>(kf);
; #pragma unroll
;                 for (int ks = 0; ks < 4; ++ks) { s[0] = MFMA32(kf[2 * ks], Qf[ks], s[0]); s[1] = MFMA32(kf[2 * ks + 1], Qf[ks], s[1]); }
;                 v_issue<1>(vb, vaddr);
;             } else {
; #pragma unroll
;             for (int ks = 0; ks < NQ; ++ks) {
;                 const unsigned chunk = mp * 8 + 2 * ks + hh;
;                 const unsigned off = kra + ((chunk ^ kswz) << 4);
;                 const bf16x8 a0 = *(const LAS bf16x8*)(Kb + off), a1 = *(const LAS bf16x8*)(Kb + off + 8192);
;                 s[0] = MFMA32(a0, Qf[ks], s[0]); s[1] = MFMA32(a1, Qf[ks], s[1]);
;             }
;             v_issue<0>(va, vaddr);
;             }
;             if (FOX) {
;                 const LAS float* cl = (const LAS float*)(lds + AL_CLS + (cur * 8 + w) * 256) + 8 * hh;
; #pragma unroll
;                 for (int blk = 0; blk < 2; ++blk)
; #pragma unroll
;                     for (int j4 = 0; j4 < 4; ++j4) { const f32x4 c = *(const LAS f32x4*)(cl + 32 * blk + 16 * (j4 >> 1) + 4 * (j4 & 1));
; #pragma unroll
;                         for (int e = 0; e < 4; ++e) s[blk][4 * j4 + e] -= c[e]; }
;             } else if (q0w - kt * 64 - 63 < 128) {
;                 const LAS float* bl = (const LAS float*)(lds + AL_BIAS);
; #pragma unroll
;                 for (int blk = 0; blk < 2; ++blk)
; #pragma unroll
;                     for (int i = 0; i < 16; ++i) { const int dist = q - (kbase + 32 * blk + 16 * (i >> 3) + (i & 7)); const int di = dist < 0 ? 0 : (dist > 128 ? 128 : dist); s[blk][i] += bl[di]; }
;             }
;             if (kt * 64 + 63 > q0w) {
; #pragma unroll
;                 for (int blk = 0; blk < 2; ++blk)
; #pragma unroll
;                     for (int i = 0; i < 16; ++i) { if (kbase + 32 * blk + 16 * (i >> 3) + (i & 7) > q) s[blk][i] = -INFINITY; }
;             }
.Lm1_fast:
	s_cmpk_lt_u32 s58, 0x100
	s_cbranch_scc0 .Lm1_fastB
	v_mfma_f32_32x32x16_bf16 v[96:111], v[2:5], v[112:115], 0
	v_mfma_f32_32x32x16_bf16 v[96:111], v[10:13], v[116:119], v[96:111]
	v_mfma_f32_32x32x16_bf16 v[96:111], v[168:171], v[120:123], v[96:111]
	v_mfma_f32_32x32x16_bf16 v[96:111], v[180:183], v[124:127], v[96:111]
	ds_read_b64_tr_b16 v[168:169], v0 offset:0x1000
	ds_read_b64_tr_b16 v[170:171], v0 offset:0x1100
	ds_read_b64_tr_b16 v[10:11], v0 offset:0x1200
	ds_read_b64_tr_b16 v[12:13], v0 offset:0x1300
	ds_read_b64_tr_b16 v[180:181], v0 offset:0x1400
	ds_read_b64_tr_b16 v[182:183], v0 offset:0x1500
	ds_read_b64_tr_b16 v[2:3], v0 offset:0x1600
	ds_read_b64_tr_b16 v[4:5], v0 offset:0x1700
	v_mfma_f32_32x32x16_bf16 v[80:95], v[6:9], v[112:115], 0
	s_nop 2
	v_exp_f32_e32 v14, v96
	v_exp_f32_e32 v15, v97
	v_mfma_f32_32x32x16_bf16 v[80:95], v[128:131], v[116:119], v[80:95]
	v_exp_f32_e32 v240, v98
	v_exp_f32_e32 v241, v99
	v_exp_f32_e32 v242, v100
	v_mfma_f32_32x32x16_bf16 v[80:95], v[172:175], v[120:123], v[80:95]
	v_exp_f32_e32 v243, v101
	v_exp_f32_e32 v244, v102
	v_exp_f32_e32 v245, v103
	v_mfma_f32_32x32x16_bf16 v[80:95], v[184:187], v[124:127], v[80:95]
	v_cvt_pk_bf16_f32 v96, v14, v15
	v_cvt_pk_bf16_f32 v97, v240, v241
	v_cvt_pk_bf16_f32 v98, v242, v243
	v_cvt_pk_bf16_f32 v99, v244, v245
	v_exp_f32_e32 v246, v104
	s_waitcnt lgkmcnt(8)
	v_mfma_f32_32x32x16_bf16 v[64:79], v[144:147], v[96:99], v[64:79]
	ds_read_b64_tr_b16 v[6:7], v0 offset:0x2000
	ds_read_b64_tr_b16 v[8:9], v0 offset:0x2100
	ds_read_b64_tr_b16 v[128:129], v0 offset:0x2200
	ds_read_b64_tr_b16 v[130:131], v0 offset:0x2300
	ds_read_b64_tr_b16 v[172:173], v0 offset:0x2400
	ds_read_b64_tr_b16 v[174:175], v0 offset:0x2500
	ds_read_b64_tr_b16 v[184:185], v0 offset:0x2600
	ds_read_b64_tr_b16 v[186:187], v0 offset:0x2700
	v_mfma_f32_32x32x16_bf16 v[48:63], v[140:143], v[96:99], v[48:63]
	v_exp_f32_e32 v247, v105
	v_exp_f32_e32 v248, v106
	v_exp_f32_e32 v249, v107
	v_mfma_f32_32x32x16_bf16 v[32:47], v[136:139], v[96:99], v[32:47]
	v_exp_f32_e32 v250, v108
	v_exp_f32_e32 v251, v109
	v_exp_f32_e32 v252, v110
	v_mfma_f32_32x32x16_bf16 v[16:31], v[132:135], v[96:99], v[16:31]
	v_exp_f32_e32 v236, v111
	v_add_f32_e32 v14, v15, v14
	v_cvt_pk_bf16_f32 v100, v246, v247
	v_cvt_pk_bf16_f32 v101, v248, v249
	v_cvt_pk_bf16_f32 v102, v250, v251
	v_add_f32_e32 v14, v240, v14
	v_cvt_pk_bf16_f32 v103, v252, v236
	v_add_f32_e32 v14, v241, v14
	s_barrier
	s_waitcnt lgkmcnt(8)
	v_mfma_f32_32x32x16_bf16 v[64:79], v[168:171], v[100:103], v[64:79]
	ds_read_b64_tr_b16 v[144:145], v0 offset:0x3000
	ds_read_b64_tr_b16 v[146:147], v0 offset:0x3100
	ds_read_b64_tr_b16 v[140:141], v0 offset:0x3200
	ds_read_b64_tr_b16 v[142:143], v0 offset:0x3300
	ds_read_b64_tr_b16 v[136:137], v0 offset:0x3400
	ds_read_b64_tr_b16 v[138:139], v0 offset:0x3500
	ds_read_b64_tr_b16 v[132:133], v0 offset:0x3600
	ds_read_b64_tr_b16 v[134:135], v0 offset:0x3700
	v_mfma_f32_32x32x16_bf16 v[48:63], v[10:13], v[100:103], v[48:63]
	v_exp_f32_e32 v104, v80
	v_exp_f32_e32 v105, v81
	v_exp_f32_e32 v106, v82
	v_mfma_f32_32x32x16_bf16 v[32:47], v[180:183], v[100:103], v[32:47]
	v_exp_f32_e32 v107, v83
	v_exp_f32_e32 v108, v84
	v_exp_f32_e32 v109, v85
	v_mfma_f32_32x32x16_bf16 v[16:31], v[2:5], v[100:103], v[16:31]
	v_exp_f32_e32 v110, v86
	v_exp_f32_e32 v111, v87
	v_cvt_pk_bf16_f32 v80, v104, v105
	v_cvt_pk_bf16_f32 v81, v106, v107
	v_cvt_pk_bf16_f32 v82, v108, v109
	v_add_f32_e32 v14, v242, v14
	v_cvt_pk_bf16_f32 v83, v110, v111
	v_add_f32_e32 v14, v243, v14
	s_waitcnt lgkmcnt(8)
	v_mfma_f32_32x32x16_bf16 v[64:79], v[6:9], v[80:83], v[64:79]
	v_exp_f32_e32 v2, v88
	v_exp_f32_e32 v3, v89
	v_exp_f32_e32 v4, v90
	v_mfma_f32_32x32x16_bf16 v[48:63], v[128:131], v[80:83], v[48:63]
	v_exp_f32_e32 v5, v91
	v_exp_f32_e32 v10, v92
	v_exp_f32_e32 v11, v93
	v_mfma_f32_32x32x16_bf16 v[32:47], v[172:175], v[80:83], v[32:47]
	v_exp_f32_e32 v12, v94
	v_exp_f32_e32 v13, v95
	v_add_f32_e32 v14, v244, v14
	v_add_f32_e32 v14, v245, v14
	v_mfma_f32_32x32x16_bf16 v[16:31], v[184:187], v[80:83], v[16:31]
	v_cvt_pk_bf16_f32 v84, v2, v3
	v_cvt_pk_bf16_f32 v85, v4, v5
	v_cvt_pk_bf16_f32 v86, v10, v11
	v_add_f32_e32 v14, v246, v14
	v_cvt_pk_bf16_f32 v87, v12, v13
	v_add_f32_e32 v14, v247, v14
	v_add_f32_e32 v14, v248, v14
	s_waitcnt lgkmcnt(0)
	v_add_f32_e32 v14, v249, v14
	v_add_f32_e32 v14, v250, v14
	v_add_f32_e32 v14, v251, v14
	v_add_f32_e32 v14, v252, v14
	v_add_f32_e32 v14, v236, v14
	s_add_i32 s41, s40, 3
	s_cmp_ge_u32 s41, s22
	s_cbranch_scc1 .Lm1f_nodma
	s_cmpk_gt_u32 s58, 0xff
	s_cbranch_scc1 .Lm1f_nodma
	v_mfma_f32_32x32x16_bf16 v[64:79], v[144:147], v[84:87], v[64:79]
	s_mov_b64 s[70:71], 0x1000
	s_add_i32 s41, s38, 0x18000
	s_and_b32 s41, s41, 0x18000
	s_add_i32 s41, s77, s41
	v_lshl_add_u64 v[240:241], v[152:153], 0, s[68:69]
	v_lshl_add_u64 v[242:243], v[240:241], 0, s[42:43]
	s_mov_b32 m0, s41
	v_lshl_add_u64 v[240:241], v[240:241], 0, s[44:45]
	global_load_lds_dwordx4 v[242:243], off
	v_mfma_f32_32x32x16_bf16 v[48:63], v[140:143], v[84:87], v[48:63]
	s_add_i32 m0, s41, 0x1000
	v_lshl_add_u64 v[242:243], v[242:243], 0, s[70:71]
	global_load_lds_dwordx4 v[242:243], off
	s_add_i32 m0, s41, 0x2000
	v_lshl_add_u64 v[242:243], v[240:241], 0, s[70:71]
	global_load_lds_dwordx4 v[240:241], off
	s_add_i32 m0, s41, 0x3000
	v_lshl_add_u64 v[240:241], v[154:155], 0, s[68:69]
	global_load_lds_dwordx4 v[242:243], off
	v_add_f32_e32 v14, v104, v14
	v_add_f32_e32 v14, v105, v14
	v_add_f32_e32 v14, v106, v14
	v_add_f32_e32 v14, v107, v14
	v_mfma_f32_32x32x16_bf16 v[32:47], v[136:139], v[84:87], v[32:47]
	v_lshl_add_u64 v[242:243], v[240:241], 0, s[48:49]
	s_add_i32 m0, s41, 0x4000
	v_lshl_add_u64 v[240:241], v[240:241], 0, s[50:51]
	global_load_lds_dwordx4 v[242:243], off
	s_add_i32 m0, s41, 0x5000
	v_lshl_add_u64 v[242:243], v[242:243], 0, s[70:71]
	global_load_lds_dwordx4 v[242:243], off
	v_add_f32_e32 v14, v108, v14
	v_add_f32_e32 v14, v109, v14
	v_add_f32_e32 v14, v110, v14
	v_add_f32_e32 v14, v111, v14
	v_add_f32_e32 v14, v2, v14
	v_add_f32_e32 v14, v3, v14
	v_mfma_f32_32x32x16_bf16 v[16:31], v[132:135], v[84:87], v[16:31]
	s_add_i32 m0, s41, 0x6000
	v_lshl_add_u64 v[242:243], v[240:241], 0, s[70:71]
	global_load_lds_dwordx4 v[240:241], off
	s_add_i32 m0, s41, 0x7000
	s_nop 0
	global_load_lds_dwordx4 v[242:243], off
	v_add_f32_e32 v14, v4, v14
	v_add_f32_e32 v14, v5, v14
	v_add_f32_e32 v14, v10, v14
	v_add_f32_e32 v14, v11, v14
	v_add_f32_e32 v14, v12, v14
	v_add_f32_e32 v14, v13, v14
	v_add_f32_e32 v163, v163, v14
	s_branch .LBB0_474

; template <int MODE>
; __device__ __forceinline__ void attn_unit(const Params& P, LAS unsigned char* lds, const int b, const int h, const int qb) {
;     ...
;             if constexpr (MODE == 1) {
;                 bf16x8 kf[8];
;                 const unsigned kb_ = (unsigned)(uintptr_t)Kb + kra, c0 = mp * 8 + hh;
;                 k_issue4(kf, kb_ + (((c0) ^ kswz) << 4), kb_ + (((c0 + 2) ^ kswz) << 4), kb_ + (((c0 + 4) ^ kswz) << 4), kb_ + (((c0 + 6) ^ kswz) << 4));
;                 v_issue<0>(va, vaddr);
;                 k_wait<8>(kf);
; #pragma unroll
;                 for (int ks = 0; ks < 4; ++ks) { s[0] = MFMA32(kf[2 * ks], Qf[ks], s[0]); s[1] = MFMA32(kf[2 * ks + 1], Qf[ks], s[1]); }
;                 v_issue<1>(vb, vaddr);
;             } else {
; #pragma unroll
;             for (int ks = 0; ks < NQ; ++ks) {
;                 const unsigned chunk = mp * 8 + 2 * ks + hh;
;                 const unsigned off = kra + ((chunk ^ kswz) << 4);
;                 const bf16x8 a0 = *(const LAS bf16x8*)(Kb + off), a1 = *(const LAS bf16x8*)(Kb + off + 8192);
;                 s[0] = MFMA32(a0, Qf[ks], s[0]); s[1] = MFMA32(a1, Qf[ks], s[1]);
;             }
;             v_issue<0>(va, vaddr);
;             }
;             if (FOX) {
;                 const LAS float* cl = (const LAS float*)(lds + AL_CLS + (cur * 8 + w) * 256) + 8 * hh;
; #pragma unroll
;                 for (int blk = 0; blk < 2; ++blk)
; #pragma unroll
;                     for (int j4 = 0; j4 < 4; ++j4) { const f32x4 c = *(const LAS f32x4*)(cl + 32 * blk + 16 * (j4 >> 1) + 4 * (j4 & 1));
; #pragma unroll
;                         for (int e = 0; e < 4; ++e) s[blk][4 * j4 + e] -= c[e]; }
;             } else if (q0w - kt * 64 - 63 < 128) {
;                 const LAS float* bl = (const LAS float*)(lds + AL_BIAS);
; #pragma unroll
;                 for (int blk = 0; blk < 2; ++blk)
; #pragma unroll
;                     for (int i = 0; i < 16; ++i) { const int dist = q - (kbase + 32 * blk + 16 * (i >> 3) + (i & 7)); const int di = dist < 0 ? 0 : (dist > 128 ? 128 : dist); s[blk][i] += bl[di]; }
;             }
;             if (kt * 64 + 63 > q0w) {
; #pragma unroll
;                 for (int blk = 0; blk < 2; ++blk)
; #pragma unroll
;                     for (int i = 0; i < 16; ++i) { if (kbase + 32 * blk + 16 * (i >> 3) + (i & 7) > q) s[blk][i] = -INFINITY; }
;             }
.Lm1_fastB:
	v_mfma_f32_32x32x16_bf16 v[96:111], v[2:5], v[112:115], 0
	v_mfma_f32_32x32x16_bf16 v[96:111], v[10:13], v[116:119], v[96:111]
	v_mfma_f32_32x32x16_bf16 v[96:111], v[168:171], v[120:123], v[96:111]
	v_mfma_f32_32x32x16_bf16 v[96:111], v[180:183], v[124:127], v[96:111]
	ds_read_b64_tr_b16 v[168:169], v0 offset:0x1000
	ds_read_b64_tr_b16 v[170:171], v0 offset:0x1100
	ds_read_b64_tr_b16 v[10:11], v0 offset:0x1200
	ds_read_b64_tr_b16 v[12:13], v0 offset:0x1300
	ds_read_b64_tr_b16 v[180:181], v0 offset:0x1400
	ds_read_b64_tr_b16 v[182:183], v0 offset:0x1500
	ds_read_b64_tr_b16 v[2:3], v0 offset:0x1600
	ds_read_b64_tr_b16 v[4:5], v0 offset:0x1700
	v_mfma_f32_32x32x16_bf16 v[80:95], v[6:9], v[112:115], 0
	s_nop 2
	v_exp_f32_e32 v14, v96
	v_exp_f32_e32 v15, v97
	v_mfma_f32_32x32x16_bf16 v[80:95], v[128:131], v[116:119], v[80:95]
	v_exp_f32_e32 v240, v98
	v_exp_f32_e32 v241, v99
	v_exp_f32_e32 v242, v100
	v_mfma_f32_32x32x16_bf16 v[80:95], v[172:175], v[120:123], v[80:95]
	v_exp_f32_e32 v243, v101
	v_exp_f32_e32 v244, v102
	v_exp_f32_e32 v245, v103
	v_mfma_f32_32x32x16_bf16 v[80:95], v[184:187], v[124:127], v[80:95]
	v_cvt_pk_bf16_f32 v96, v14, v15
	v_cvt_pk_bf16_f32 v97, v240, v241
	v_cvt_pk_bf16_f32 v98, v242, v243
	v_cvt_pk_bf16_f32 v99, v244, v245
	v_exp_f32_e32 v246, v104
	s_waitcnt lgkmcnt(8)
	v_mfma_f32_32x32x16_bf16 v[64:79], v[144:147], v[96:99], v[64:79]
	ds_read_b64_tr_b16 v[6:7], v0 offset:0x2000
	ds_read_b64_tr_b16 v[8:9], v0 offset:0x2100
	ds_read_b64_tr_b16 v[128:129], v0 offset:0x2200
	ds_read_b64_tr_b16 v[130:131], v0 offset:0x2300
	ds_read_b64_tr_b16 v[172:173], v0 offset:0x2400
	ds_read_b64_tr_b16 v[174:175], v0 offset:0x2500
	ds_read_b64_tr_b16 v[184:185], v0 offset:0x2600
	ds_read_b64_tr_b16 v[186:187], v0 offset:0x2700
	v_mfma_f32_32x32x16_bf16 v[48:63], v[140:143], v[96:99], v[48:63]
	v_exp_f32_e32 v247, v105
	v_exp_f32_e32 v248, v106
	v_exp_f32_e32 v249, v107
	v_mfma_f32_32x32x16_bf16 v[32:47], v[136:139], v[96:99], v[32:47]
	v_exp_f32_e32 v250, v108
	v_exp_f32_e32 v251, v109
	v_exp_f32_e32 v252, v110
	v_mfma_f32_32x32x16_bf16 v[16:31], v[132:135], v[96:99], v[16:31]
	v_exp_f32_e32 v236, v111
	v_add_f32_e32 v14, v15, v14
	v_cvt_pk_bf16_f32 v100, v246, v247
	v_cvt_pk_bf16_f32 v101, v248, v249
	v_cvt_pk_bf16_f32 v102, v250, v251
	v_add_f32_e32 v14, v240, v14
	v_cvt_pk_bf16_f32 v103, v252, v236
	v_add_f32_e32 v14, v241, v14
	s_branch .LBB0_474
